# adds: MLA loop QK phase waits once per 32-key block for its K fragments instead of before every MFMA
# baseline (speedup 1.0000x reference)
; DI float fexp2(float x) { return __builtin_amdgcn_exp2f(x); }
; #define AT_LDK(dst, k4_) _Pragma("unroll") for (int kc = 0; kc < NKC; ++kc) dst[kc] = *(const LAS bf16x8*)(kb + (((k4_) * 32 + r) * KS + kc * 16 + hh * 8) * 2)
; #define AT_MMK(src, k4_) do { _Pragma("unroll") for (int i = 0; i < 16; ++i) s[k4_][i] = 0.f; _Pragma("unroll") for (int kc = 0; kc < NKC; ++kc) s[k4_] = MFMA32(src[kc], qf[kc], s[k4_]); } while (0)
; template <int DK> ...
;     ...
;       { bf16x8 ka[NKC], kb2[NKC];
;         AT_LDK(ka, 0); __builtin_amdgcn_sched_barrier(0);
;         AT_LDK(kb2, 1); __builtin_amdgcn_sched_barrier(0); AT_MMK(ka, 0); __builtin_amdgcn_sched_barrier(0);
;         AT_LDK(ka, 2); __builtin_amdgcn_sched_barrier(0); AT_MMK(kb2, 1); __builtin_amdgcn_sched_barrier(0);
;         AT_LDK(kb2, 3); __builtin_amdgcn_sched_barrier(0); AT_MMK(ka, 2); __builtin_amdgcn_sched_barrier(0);
;         AT_MMK(kb2, 3); __builtin_amdgcn_sched_barrier(0); }
;     ...
;       if (masked) {
; #pragma unroll
;         for (int k4 = 0; k4 < 4; ++k4)
; #pragma unroll
;           for (int i = 0; i < 16; ++i) { const int dd = (tq0 + r) - (kpos_t + k4 * 32 + (i & 3) + 8 * (i >> 2) + 4 * hh); if (dd > 128 || dd < -128) s[k4][i] = -1e30f; }
;       }
;       float mx = -3e38f;
; #pragma unroll
;       for (int k4 = 0; k4 < 4; ++k4)
; #pragma unroll
;         for (int i = 0; i < 16; i += 2) mx = fmaxf(fmaxf(mx, s[k4][i]), s[k4][i + 1]);
;       mx = fmaxf(mx, __shfl_xor(mx, 32));
;       const float mnew = fmaxf(mrun, mx * cq), alpha = fexp2(mrun - mnew); mrun = mnew;
;       f32x2 ls2 = {0.f, 0.f}; const f32x2 cq2 = {cq, cq}, mn2 = {-mnew, -mnew};
; #pragma unroll
;       for (int k4 = 0; k4 < 4; ++k4)
; #pragma unroll
;         for (int i = 0; i < 16; i += 2) {
;           f32x2 xv = {s[k4][i], s[k4][i + 1]}; xv = xv * cq2 + mn2;
;           f32x2 pv = {fexp2(xv[0]), fexp2(xv[1])}; s[k4][i] = pv[0]; s[k4][i + 1] = pv[1]; ls2 += pv;
;         }
;       lrun = lrun * alpha + (ls2[0] + ls2[1]);
;       if (__builtin_amdgcn_ballot_w64(alpha != 1.f) != 0ull) { o0 *= alpha; o1 *= alpha; }
.LBB0_754:
	s_and_b32 s1, s6, 1
	s_mul_i32 s6, s1, 0xaa00
	s_add_i32 s6, s6, 0
	v_add3_u32 v162, s6, v146, v165
	ds_read_b128 v[34:37], v162
	ds_read_b128 v[38:41], v162 offset:32
	ds_read_b128 v[42:45], v162 offset:64
	ds_read_b128 v[46:49], v162 offset:96
	ds_read_b128 v[50:53], v162 offset:128
	ds_read_b128 v[54:57], v162 offset:160
	ds_read_b128 v[58:61], v162 offset:6656
	ds_read_b128 v[62:65], v162 offset:6688
	ds_read_b128 v[170:173], v162 offset:6720
	ds_read_b128 v[174:177], v162 offset:6752
	ds_read_b128 v[178:181], v162 offset:6784
	ds_read_b128 v[182:185], v162 offset:6816
	s_waitcnt lgkmcnt(6)
	v_mfma_f32_32x32x16_bf16 v[82:97], v[34:37], v[118:121], 0
	v_mfma_f32_32x32x16_bf16 v[82:97], v[38:41], v[98:101], v[82:97]
	v_mfma_f32_32x32x16_bf16 v[82:97], v[42:45], v[102:105], v[82:97]
	v_mfma_f32_32x32x16_bf16 v[82:97], v[46:49], v[106:109], v[82:97]
	v_mfma_f32_32x32x16_bf16 v[82:97], v[50:53], v[110:113], v[82:97]
	v_mfma_f32_32x32x16_bf16 v[82:97], v[54:57], v[114:117], v[82:97]
	ds_read_b128 v[34:37], v162 offset:13312
	ds_read_b128 v[38:41], v162 offset:13344
	ds_read_b128 v[42:45], v162 offset:13376
	ds_read_b128 v[46:49], v162 offset:13408
	ds_read_b128 v[202:205], v162 offset:13440
	ds_read_b128 v[206:209], v162 offset:13472
	s_waitcnt lgkmcnt(6)
	v_mfma_f32_32x32x16_bf16 v[66:81], v[58:61], v[118:121], 0
	v_mfma_f32_32x32x16_bf16 v[66:81], v[62:65], v[98:101], v[66:81]
	v_mfma_f32_32x32x16_bf16 v[66:81], v[170:173], v[102:105], v[66:81]
	v_mfma_f32_32x32x16_bf16 v[66:81], v[174:177], v[106:109], v[66:81]
	v_mfma_f32_32x32x16_bf16 v[66:81], v[178:181], v[110:113], v[66:81]
	v_mfma_f32_32x32x16_bf16 v[66:81], v[182:185], v[114:117], v[66:81]
	ds_read_b128 v[170:173], v162 offset:19968
	ds_read_b128 v[174:177], v162 offset:20000
	ds_read_b128 v[178:181], v162 offset:20032
	ds_read_b128 v[182:185], v162 offset:20064
	ds_read_b128 v[210:213], v162 offset:20096
	ds_read_b128 v[226:229], v162 offset:20128
	s_waitcnt lgkmcnt(6)
	v_mfma_f32_32x32x16_bf16 v[50:65], v[34:37], v[118:121], 0
	v_max3_f32 v162, v82, s56, v83
	v_max3_f32 v162, v162, v84, v85
	v_mfma_f32_32x32x16_bf16 v[50:65], v[38:41], v[98:101], v[50:65]
	v_max3_f32 v162, v162, v86, v87
	v_max3_f32 v162, v162, v88, v89
	v_mfma_f32_32x32x16_bf16 v[50:65], v[42:45], v[102:105], v[50:65]
	v_max3_f32 v162, v162, v90, v91
	v_max3_f32 v162, v162, v92, v93
	v_mfma_f32_32x32x16_bf16 v[50:65], v[46:49], v[106:109], v[50:65]
	v_max3_f32 v162, v162, v94, v95
	v_max3_f32 v162, v162, v96, v97
	v_mfma_f32_32x32x16_bf16 v[50:65], v[202:205], v[110:113], v[50:65]
	v_max3_f32 v162, v162, v66, v67
	v_max3_f32 v162, v162, v68, v69
	v_mfma_f32_32x32x16_bf16 v[50:65], v[206:209], v[114:117], v[50:65]
	v_max3_f32 v162, v162, v70, v71
	v_max3_f32 v162, v162, v72, v73
	s_waitcnt lgkmcnt(0)
	v_mfma_f32_32x32x16_bf16 v[34:49], v[170:173], v[118:121], 0
	v_max3_f32 v162, v162, v74, v75
	v_max3_f32 v162, v162, v76, v77
	v_mfma_f32_32x32x16_bf16 v[34:49], v[174:177], v[98:101], v[34:49]
	v_max3_f32 v162, v162, v78, v79
	v_max3_f32 v162, v162, v80, v81
	v_mfma_f32_32x32x16_bf16 v[34:49], v[178:181], v[102:105], v[34:49]
	v_add3_u32 v169, s6, v164, v168
	v_add_u32_e32 v190, 0x6800, v169
	v_add_u32_e32 v169, 0x8800, v169
	v_mfma_f32_32x32x16_bf16 v[34:49], v[182:185], v[106:109], v[34:49]
	v_max3_f32 v162, v162, v50, v51
	v_max3_f32 v162, v162, v52, v53
	v_mfma_f32_32x32x16_bf16 v[34:49], v[210:213], v[110:113], v[34:49]
	v_max3_f32 v162, v162, v54, v55
	v_max3_f32 v162, v162, v56, v57
	v_mfma_f32_32x32x16_bf16 v[34:49], v[226:229], v[114:117], v[34:49]
	v_max3_f32 v162, v162, v58, v59
	v_max3_f32 v162, v162, v60, v61
	v_max3_f32 v162, v162, v62, v63
	v_max3_f32 v162, v162, v64, v65
	ds_read2_b64 v[170:173], v190 offset1:2
	ds_read2_b64 v[174:177], v190 offset0:4 offset1:6
	ds_read2_b64 v[178:181], v169 offset0:32 offset1:34
	ds_read2_b64 v[182:185], v169 offset0:36 offset1:38
	s_nop 3
	v_max3_f32 v162, v162, v34, v35
	v_max3_f32 v162, v162, v36, v37
	v_max3_f32 v162, v162, v38, v39
	v_max3_f32 v162, v162, v40, v41
	v_max3_f32 v162, v162, v42, v43
	v_max3_f32 v162, v162, v44, v45
	v_max3_f32 v162, v162, v46, v47
	v_max3_f32 v162, v162, v48, v49
	v_mov_b32_e32 v210, v162
	s_nop 1
	v_permlane32_swap_b32_e32 v210, v162
	s_nop 0
	v_max_f32_e32 v162, v162, v210
	v_mul_f32_e32 v162, v150, v162
	v_max_f32_e32 v210, v160, v160
	v_max_f32_e32 v162, v210, v162
	v_sub_f32_e32 v160, v160, v162
	v_exp_f32_e32 v160, v160
	s_nop 0
	v_cmp_neq_f32_e32 vcc, 1.0, v160
	s_cbranch_vccz .Lmla_norescale
	v_pk_mul_f32 v[32:33], v[32:33], v[160:161] op_sel_hi:[1,0]
	v_pk_mul_f32 v[30:31], v[30:31], v[160:161] op_sel_hi:[1,0]
	v_pk_mul_f32 v[28:29], v[28:29], v[160:161] op_sel_hi:[1,0]
	v_pk_mul_f32 v[26:27], v[26:27], v[160:161] op_sel_hi:[1,0]
	v_pk_mul_f32 v[24:25], v[24:25], v[160:161] op_sel_hi:[1,0]
	v_pk_mul_f32 v[22:23], v[22:23], v[160:161] op_sel_hi:[1,0]
	v_pk_mul_f32 v[20:21], v[20:21], v[160:161] op_sel_hi:[1,0]
	v_pk_mul_f32 v[18:19], v[18:19], v[160:161] op_sel_hi:[1,0]
	v_pk_mul_f32 v[16:17], v[16:17], v[160:161] op_sel_hi:[1,0]
	v_pk_mul_f32 v[14:15], v[14:15], v[160:161] op_sel_hi:[1,0]
	v_pk_mul_f32 v[12:13], v[12:13], v[160:161] op_sel_hi:[1,0]
	v_pk_mul_f32 v[10:11], v[10:11], v[160:161] op_sel_hi:[1,0]
	v_pk_mul_f32 v[8:9], v[8:9], v[160:161] op_sel_hi:[1,0]
	v_pk_mul_f32 v[6:7], v[6:7], v[160:161] op_sel_hi:[1,0]
	v_pk_mul_f32 v[4:5], v[4:5], v[160:161] op_sel_hi:[1,0]
	v_pk_mul_f32 v[2:3], v[2:3], v[160:161] op_sel_hi:[1,0]
